# DA unit: diagonal (first) key tile hand-written: 4 QK blocks with the ALiBi |i-j| bias as MFMA accumulator input, one row max, then exp/PV per block (replaces the compiler's sequential online-softmax
# speedup vs baseline: 1.1114x; 1.0028x over previous
; __device__ void da_unit(char* lds, const Params& p, int layer, int unit) {
;     ...
;     const int pr = (r & 0x13) | ((r & 4) << 1) | ((r & 8) >> 1);
;     if (wid >= 4) __builtin_amdgcn_s_setprio(1);
;     {
;         const int it = 0; const int kt = qb;
;         const char* cK = lds + (it & 1) * DA_STAGE;
;         const char* cV = cK + DA_KBYTES;
;         char* nK = lds + ((it + 1) & 1) * DA_STAGE;
;         if (it + 1 < NT) {
;             const int tn = tile_of(it + 1);
; #pragma unroll
;             for (int j = 0; j < 4; ++j) { rk[j] = *(const u32x4*)(Kg + (size_t)tn * 16384 + j * 4096); rv[j] = *(const u32x4*)(Vg + (size_t)tn * 16384 + j * 4096); }
;         }
; #pragma unroll
;         for (int kb = 0; kb < 4; ++kb) {
;             const int k0 = kt * 128 + kb * 32;
;             f32x16 s; const float A = 0.f;
;             const float kq = (float)k0 + qrel;
; #pragma unroll
;             for (int e = 0; e < 16; ++e) s[e] = 0.f;
; #pragma unroll
;             for (int t = 0; t < 4; ++t) {
;                 const bf16x8 kf = *(const bf16x8*)(cK + (kb * 32 + pr) * DA_KP + c * 128 + t * 32 + h2 * 16);
;                 s = __builtin_amdgcn_mfma_f32_32x32x16_bf16(kf, qf[t], s, 0, 0, 0);
;             }
; #pragma unroll
;             for (int e = 0; e < 16; ++e) s[e] = fmaf(fabsf(kq + (float)(16 * (e >> 3) + (e & 7))), -slope2, s[e]);
.LBB0_478:
	v_ldexp_f32 v19, 1.0, s1
	s_mov_b32 s10, 0x3e38aa3b
	v_mul_f32_e32 v65, 0x3fb8aa3b, v19
	s_add_i32 s0, s14, 1
	s_cmp_lg_u32 s14, 15
	s_cselect_b32 s0, s0, 14
	s_lshl_b32 s18, s0, 15
	s_mov_b32 s19, 0
	v_lshl_add_u64 v[156:157], v[148:149], 0, s[18:19]
	global_load_dwordx4 v[130:133], v[156:157], off
	s_add_u32 s18, s18, 0x2000
	v_lshl_add_u64 v[156:157], v[148:149], 0, s[18:19]
	global_load_dwordx4 v[134:137], v[156:157], off
	s_add_u32 s18, s18, 0x2000
	v_lshl_add_u64 v[156:157], v[148:149], 0, s[18:19]
	global_load_dwordx4 v[138:141], v[156:157], off
	s_add_u32 s18, s18, 0x2000
	v_lshl_add_u64 v[156:157], v[148:149], 0, s[18:19]
	global_load_dwordx4 v[142:145], v[156:157], off
	s_lshl_b32 s18, s0, 15
	s_mov_b32 s19, 0
	v_lshl_add_u64 v[156:157], v[150:151], 0, s[18:19]
	global_load_dwordx4 v[66:69], v[156:157], off
	s_add_u32 s18, s18, 0x2000
	v_lshl_add_u64 v[156:157], v[150:151], 0, s[18:19]
	global_load_dwordx4 v[70:73], v[156:157], off
	s_add_u32 s18, s18, 0x2000
	v_lshl_add_u64 v[156:157], v[150:151], 0, s[18:19]
	global_load_dwordx4 v[74:77], v[156:157], off
	s_add_u32 s18, s18, 0x2000
	v_lshl_add_u64 v[156:157], v[150:151], 0, s[18:19]
	global_load_dwordx4 v[78:81], v[156:157], off
	v_lshlrev_b32_e32 v242, 1, v187
	v_and_b32_e32 v242, 8, v242
	v_lshrrev_b32_e32 v253, 1, v187
	v_and_b32_e32 v253, 4, v253
	v_and_b32_e32 v241, 19, v187
	v_or3_b32 v241, v242, v241, v253
	v_mul_u32_u24_e32 v186, 0x110, v241
	v_mul_u32_u24_e32 v154, 0x90, v147
	v_add_u32_e32 v168, 0x3600, v154
	v_lshlrev_b32_e32 v252, 3, v188
	v_cvt_f32_ubyte0_e32 v242, v252
	v_or_b32_e32 v253, s7, v147
	v_cvt_f32_i32_e32 v253, v253
	v_sub_f32_e32 v185, v242, v253
	v_add3_u32 v234, s8, v186, v152
	s_mov_b32 s2, 0x8800
	v_add3_u32 v235, s2, v152, v154
	s_lshl_b32 s11, s14, 7
	ds_read_b128 v[210:213], v234 offset:0
	ds_read_b128 v[214:217], v234 offset:32
	ds_read_b128 v[218:221], v234 offset:64
	ds_read_b128 v[222:225], v234 offset:96
	s_waitcnt vmcnt(11)
	v_lshlrev_b32_e32 v242, 16, v8
	v_and_b32_e32 v253, 0xffff0000, v8
	v_mul_f32_e32 v242, s10, v242
	v_mul_f32_e32 v253, s10, v253
	v_cvt_pk_bf16_f32 v114, v242, v253
	v_lshlrev_b32_e32 v241, 16, v9
	v_and_b32_e32 v236, 0xffff0000, v9
	v_mul_f32_e32 v241, s10, v241
	v_mul_f32_e32 v236, s10, v236
	v_cvt_pk_bf16_f32 v115, v241, v236
	v_lshlrev_b32_e32 v242, 16, v10
	v_and_b32_e32 v253, 0xffff0000, v10
	v_mul_f32_e32 v242, s10, v242
	v_mul_f32_e32 v253, s10, v253
	v_cvt_pk_bf16_f32 v116, v242, v253
	v_lshlrev_b32_e32 v241, 16, v11
	v_and_b32_e32 v236, 0xffff0000, v11
	v_mul_f32_e32 v241, s10, v241
	v_mul_f32_e32 v236, s10, v236
	v_cvt_pk_bf16_f32 v117, v241, v236
	s_waitcnt vmcnt(10)
	v_lshlrev_b32_e32 v242, 16, v4
	v_and_b32_e32 v253, 0xffff0000, v4
	v_mul_f32_e32 v242, s10, v242
	v_mul_f32_e32 v253, s10, v253
	v_cvt_pk_bf16_f32 v118, v242, v253
	v_lshlrev_b32_e32 v241, 16, v5
	v_and_b32_e32 v236, 0xffff0000, v5
	v_mul_f32_e32 v241, s10, v241
	v_mul_f32_e32 v236, s10, v236
	v_cvt_pk_bf16_f32 v119, v241, v236
	v_lshlrev_b32_e32 v242, 16, v6
	v_and_b32_e32 v253, 0xffff0000, v6
	v_mul_f32_e32 v242, s10, v242
	v_mul_f32_e32 v253, s10, v253
	v_cvt_pk_bf16_f32 v120, v242, v253
	v_lshlrev_b32_e32 v241, 16, v7
	v_and_b32_e32 v236, 0xffff0000, v7
	v_mul_f32_e32 v241, s10, v241
	v_mul_f32_e32 v236, s10, v236
	v_cvt_pk_bf16_f32 v121, v241, v236
	s_waitcnt vmcnt(9)
	v_lshlrev_b32_e32 v242, 16, v0
	v_and_b32_e32 v253, 0xffff0000, v0
	v_mul_f32_e32 v242, s10, v242
	v_mul_f32_e32 v253, s10, v253
	v_cvt_pk_bf16_f32 v122, v242, v253
	v_lshlrev_b32_e32 v241, 16, v1
	v_and_b32_e32 v236, 0xffff0000, v1
	v_mul_f32_e32 v241, s10, v241
	v_mul_f32_e32 v236, s10, v236
	v_cvt_pk_bf16_f32 v123, v241, v236
	v_lshlrev_b32_e32 v242, 16, v2
	v_and_b32_e32 v253, 0xffff0000, v2
	v_mul_f32_e32 v242, s10, v242
	v_mul_f32_e32 v253, s10, v253
	v_cvt_pk_bf16_f32 v124, v242, v253
	v_lshlrev_b32_e32 v241, 16, v3
	v_and_b32_e32 v236, 0xffff0000, v3
	v_mul_f32_e32 v241, s10, v241
	v_mul_f32_e32 v236, s10, v236
	v_cvt_pk_bf16_f32 v125, v241, v236
	s_waitcnt vmcnt(8)
	v_lshlrev_b32_e32 v242, 16, v14
	v_and_b32_e32 v253, 0xffff0000, v14
	v_mul_f32_e32 v242, s10, v242
	v_mul_f32_e32 v253, s10, v253
	v_cvt_pk_bf16_f32 v126, v242, v253
	v_lshlrev_b32_e32 v241, 16, v15
	v_and_b32_e32 v236, 0xffff0000, v15
	v_mul_f32_e32 v241, s10, v241
	v_mul_f32_e32 v236, s10, v236
	v_cvt_pk_bf16_f32 v127, v241, v236
	v_lshlrev_b32_e32 v242, 16, v16
	v_and_b32_e32 v253, 0xffff0000, v16
	v_mul_f32_e32 v242, s10, v242
	v_mul_f32_e32 v253, s10, v253
	v_cvt_pk_bf16_f32 v128, v242, v253
	v_lshlrev_b32_e32 v241, 16, v17
	v_and_b32_e32 v236, 0xffff0000, v17
	v_mul_f32_e32 v241, s10, v241
	v_mul_f32_e32 v236, s10, v236
	v_cvt_pk_bf16_f32 v129, v241, v236
	s_mov_b32 s2, s11
	v_cvt_f32_u32_e32 v239, s2
	v_add_f32_e32 v239, v185, v239
	v_mul_f32_e64 v82, |v239|, -v65
	v_add_f32_e32 v253, 1.0, v239
	v_mul_f32_e64 v83, |v253|, -v65
	v_add_f32_e32 v253, 2.0, v239
	v_mul_f32_e64 v84, |v253|, -v65
	v_add_f32_e32 v253, 0x40400000, v239
	v_mul_f32_e64 v85, |v253|, -v65
	v_add_f32_e32 v253, 4.0, v239
	v_mul_f32_e64 v86, |v253|, -v65
	v_add_f32_e32 v253, 0x40a00000, v239
	v_mul_f32_e64 v87, |v253|, -v65
	v_add_f32_e32 v253, 0x40c00000, v239
	v_mul_f32_e64 v88, |v253|, -v65
	v_add_f32_e32 v253, 0x40e00000, v239
	v_mul_f32_e64 v89, |v253|, -v65
	v_add_f32_e32 v253, 0x41800000, v239
	v_mul_f32_e64 v90, |v253|, -v65
	v_add_f32_e32 v253, 0x41880000, v239
	v_mul_f32_e64 v91, |v253|, -v65
	v_add_f32_e32 v253, 0x41900000, v239
	v_mul_f32_e64 v92, |v253|, -v65
	v_add_f32_e32 v253, 0x41980000, v239
	v_mul_f32_e64 v93, |v253|, -v65
	v_add_f32_e32 v253, 0x41a00000, v239
	v_mul_f32_e64 v94, |v253|, -v65
	v_add_f32_e32 v253, 0x41a80000, v239
	v_mul_f32_e64 v95, |v253|, -v65
	v_add_f32_e32 v253, 0x41b00000, v239
	v_mul_f32_e64 v96, |v253|, -v65
	v_add_f32_e32 v253, 0x41b80000, v239
	v_mul_f32_e64 v97, |v253|, -v65
	s_waitcnt lgkmcnt(3)
; __device__ void da_unit(char* lds, const Params& p, int layer, int unit) {
;     ...
;         for (int kb = 0; kb < 4; ++kb) {
;             const int k0 = kt * 128 + kb * 32;
;             f32x16 s; const float A = 0.f;
;             const float kq = (float)k0 + qrel;
; #pragma unroll
;             for (int e = 0; e < 16; ++e) s[e] = 0.f;
; #pragma unroll
;             for (int t = 0; t < 4; ++t) {
;                 const bf16x8 kf = *(const bf16x8*)(cK + (kb * 32 + pr) * DA_KP + c * 128 + t * 32 + h2 * 16);
;                 s = __builtin_amdgcn_mfma_f32_32x32x16_bf16(kf, qf[t], s, 0, 0, 0);
;             }
; #pragma unroll
;             for (int e = 0; e < 16; ++e) s[e] = fmaf(fabsf(kq + (float)(16 * (e >> 3) + (e & 7))), -slope2, s[e]);
	s_nop 0
	v_mfma_f32_32x32x16_bf16 v[82:97], v[210:213], v[114:117], v[82:97]
	ds_read_b128 v[210:213], v234 offset:8704
	s_add_i32 s2, s11, 32
	v_cvt_f32_u32_e32 v236, s2
	v_add_f32_e32 v236, v185, v236
	v_mul_f32_e64 v98, |v236|, -v65
	v_add_f32_e32 v253, 1.0, v236
	v_mul_f32_e64 v99, |v253|, -v65
	v_add_f32_e32 v253, 2.0, v236
	v_mul_f32_e64 v100, |v253|, -v65
	v_add_f32_e32 v253, 0x40400000, v236
	s_waitcnt lgkmcnt(3)
	v_mfma_f32_32x32x16_bf16 v[82:97], v[214:217], v[118:121], v[82:97]
	ds_read_b128 v[214:217], v234 offset:8736
	v_mul_f32_e64 v101, |v253|, -v65
	v_add_f32_e32 v253, 4.0, v236
	v_mul_f32_e64 v102, |v253|, -v65
	v_add_f32_e32 v253, 0x40a00000, v236
	v_mul_f32_e64 v103, |v253|, -v65
	v_add_f32_e32 v253, 0x40c00000, v236
	v_mul_f32_e64 v104, |v253|, -v65
	v_add_f32_e32 v253, 0x40e00000, v236
	v_mul_f32_e64 v105, |v253|, -v65
	s_waitcnt lgkmcnt(3)
	v_mfma_f32_32x32x16_bf16 v[82:97], v[218:221], v[122:125], v[82:97]
	ds_read_b128 v[218:221], v234 offset:8768
	v_add_f32_e32 v253, 0x41800000, v236
	v_mul_f32_e64 v106, |v253|, -v65
	v_add_f32_e32 v253, 0x41880000, v236
	v_mul_f32_e64 v107, |v253|, -v65
	v_add_f32_e32 v253, 0x41900000, v236
	v_mul_f32_e64 v108, |v253|, -v65
	v_add_f32_e32 v253, 0x41980000, v236
	v_mul_f32_e64 v109, |v253|, -v65
	v_add_f32_e32 v253, 0x41a00000, v236
	s_waitcnt lgkmcnt(3)
	v_mfma_f32_32x32x16_bf16 v[82:97], v[222:225], v[126:129], v[82:97]
	ds_read_b128 v[222:225], v234 offset:8800
	v_mul_f32_e64 v110, |v253|, -v65
	v_add_f32_e32 v253, 0x41a80000, v236
	v_mul_f32_e64 v111, |v253|, -v65
	v_add_f32_e32 v253, 0x41b00000, v236
	v_mul_f32_e64 v112, |v253|, -v65
	v_add_f32_e32 v253, 0x41b80000, v236
	v_mul_f32_e64 v113, |v253|, -v65
	s_waitcnt lgkmcnt(3)
	s_nop 0
	v_mfma_f32_32x32x16_bf16 v[98:113], v[210:213], v[114:117], v[98:113]
	ds_read_b128 v[210:213], v234 offset:17408
	s_add_i32 s2, s11, 64
	v_cvt_f32_u32_e32 v239, s2
	v_add_f32_e32 v239, v185, v239
	v_mul_f32_e64 v16, |v239|, -v65
	v_add_f32_e32 v253, 1.0, v239
	v_mul_f32_e64 v17, |v253|, -v65
	v_add_f32_e32 v253, 2.0, v239
	v_mul_f32_e64 v18, |v253|, -v65
	v_add_f32_e32 v253, 0x40400000, v239
	s_waitcnt lgkmcnt(3)
	v_mfma_f32_32x32x16_bf16 v[98:113], v[214:217], v[118:121], v[98:113]
	ds_read_b128 v[214:217], v234 offset:17440
	v_mul_f32_e64 v19, |v253|, -v65
	v_add_f32_e32 v253, 4.0, v239
	v_mul_f32_e64 v20, |v253|, -v65
	v_add_f32_e32 v253, 0x40a00000, v239
	v_mul_f32_e64 v21, |v253|, -v65
	v_add_f32_e32 v253, 0x40c00000, v239
	v_mul_f32_e64 v22, |v253|, -v65
	v_add_f32_e32 v253, 0x40e00000, v239
	v_mul_f32_e64 v23, |v253|, -v65
	s_waitcnt lgkmcnt(3)
	v_mfma_f32_32x32x16_bf16 v[98:113], v[218:221], v[122:125], v[98:113]
	ds_read_b128 v[218:221], v234 offset:17472
	v_add_f32_e32 v253, 0x41800000, v239
	v_mul_f32_e64 v24, |v253|, -v65
	v_add_f32_e32 v253, 0x41880000, v239
	v_mul_f32_e64 v25, |v253|, -v65
	v_add_f32_e32 v253, 0x41900000, v239
	v_mul_f32_e64 v26, |v253|, -v65
	v_add_f32_e32 v253, 0x41980000, v239
	v_mul_f32_e64 v27, |v253|, -v65
	v_add_f32_e32 v253, 0x41a00000, v239
	s_waitcnt lgkmcnt(3)
	v_mfma_f32_32x32x16_bf16 v[98:113], v[222:225], v[126:129], v[98:113]
	ds_read_b128 v[222:225], v234 offset:17504
	v_mul_f32_e64 v28, |v253|, -v65
	v_add_f32_e32 v253, 0x41a80000, v239
	v_mul_f32_e64 v29, |v253|, -v65
	v_add_f32_e32 v253, 0x41b00000, v239
	v_mul_f32_e64 v30, |v253|, -v65
	v_add_f32_e32 v253, 0x41b80000, v239
	v_mul_f32_e64 v31, |v253|, -v65
	s_waitcnt lgkmcnt(3)
	s_nop 0
	v_mfma_f32_32x32x16_bf16 v[16:31], v[210:213], v[114:117], v[16:31]
	ds_read_b128 v[210:213], v234 offset:26112
	s_add_i32 s2, s11, 96
	v_cvt_f32_u32_e32 v236, s2
	v_add_f32_e32 v236, v185, v236
	v_mul_f32_e64 v0, |v236|, -v65
	v_add_f32_e32 v253, 1.0, v236
	v_mul_f32_e64 v1, |v253|, -v65
	v_add_f32_e32 v253, 2.0, v236
	v_mul_f32_e64 v2, |v253|, -v65
	v_add_f32_e32 v253, 0x40400000, v236
	s_waitcnt lgkmcnt(3)
	v_mfma_f32_32x32x16_bf16 v[16:31], v[214:217], v[118:121], v[16:31]
	ds_read_b128 v[214:217], v234 offset:26144
	v_mul_f32_e64 v3, |v253|, -v65
	v_add_f32_e32 v253, 4.0, v236
	v_mul_f32_e64 v4, |v253|, -v65
	v_add_f32_e32 v253, 0x40a00000, v236
	v_mul_f32_e64 v5, |v253|, -v65
	v_add_f32_e32 v253, 0x40c00000, v236
	v_mul_f32_e64 v6, |v253|, -v65
	v_add_f32_e32 v253, 0x40e00000, v236
	v_mul_f32_e64 v7, |v253|, -v65
	s_waitcnt lgkmcnt(3)
	v_mfma_f32_32x32x16_bf16 v[16:31], v[218:221], v[122:125], v[16:31]
	ds_read_b128 v[218:221], v234 offset:26176
	v_add_f32_e32 v253, 0x41800000, v236
	v_mul_f32_e64 v8, |v253|, -v65
	v_add_f32_e32 v253, 0x41880000, v236
	v_mul_f32_e64 v9, |v253|, -v65
	v_add_f32_e32 v253, 0x41900000, v236
	v_mul_f32_e64 v10, |v253|, -v65
	v_add_f32_e32 v253, 0x41980000, v236
	v_mul_f32_e64 v11, |v253|, -v65
	v_add_f32_e32 v253, 0x41a00000, v236
	s_waitcnt lgkmcnt(3)
	v_mfma_f32_32x32x16_bf16 v[16:31], v[222:225], v[126:129], v[16:31]
	ds_read_b128 v[222:225], v234 offset:26208
	v_mul_f32_e64 v12, |v253|, -v65
	v_add_f32_e32 v253, 0x41a80000, v236
	v_mul_f32_e64 v13, |v253|, -v65
	v_add_f32_e32 v253, 0x41b00000, v236
	v_mul_f32_e64 v14, |v253|, -v65
	v_add_f32_e32 v253, 0x41b80000, v236
	v_mul_f32_e64 v15, |v253|, -v65
	s_waitcnt lgkmcnt(3)
	s_nop 0
	v_mfma_f32_32x32x16_bf16 v[0:15], v[210:213], v[114:117], v[0:15]
	s_waitcnt lgkmcnt(2)
	v_mfma_f32_32x32x16_bf16 v[0:15], v[214:217], v[118:121], v[0:15]
	s_waitcnt lgkmcnt(1)
	v_mfma_f32_32x32x16_bf16 v[0:15], v[218:221], v[122:125], v[0:15]
	s_waitcnt lgkmcnt(0)
; __device__ __forceinline__ float fast_exp2(float x) { return __builtin_amdgcn_exp2f(x); }
; __device__ void da_unit(char* lds, const Params& p, int layer, int unit) {
;     ...
;             float mx = s[0];
; #pragma unroll
;             for (int e = 1; e < 16; ++e) mx = fmaxf(mx, s[e]);
;             mx += A;
;             mx = fmaxf(mx, __shfl_xor(mx, 32));
;             if (!__all(mx <= mrow + 8.0f)) {
;                 const float mnew = fmaxf(mrow, mx);
;                 const float alpha = fast_exp2(mrow - mnew);
; #pragma unroll
;                 for (int k = 0; k < 4; ++k) O[k] = O[k] * alpha;
;                 lrow *= alpha; mrow = mnew;
;             }
;             const float mm = mrow - A;
;             float ps = 0.f;
; #pragma unroll
;             for (int e = 0; e < 16; ++e) { s[e] = fast_exp2(s[e] - mm); ps += s[e]; }
;             lrow += ps;
;             bf16x8 pb[2];
; #pragma unroll
;             for (int sp = 0; sp < 2; ++sp) {
;                 u32x4 w;
;                 w.x = cvt_pk_bf16(s[8 * sp + 0], s[8 * sp + 1]); w.y = cvt_pk_bf16(s[8 * sp + 2], s[8 * sp + 3]);
;                 w.z = cvt_pk_bf16(s[8 * sp + 4], s[8 * sp + 5]); w.w = cvt_pk_bf16(s[8 * sp + 6], s[8 * sp + 7]);
;                 pb[sp] = __builtin_bit_cast(bf16x8, w);
;             }
; #pragma unroll
;             for (int sp = 0; sp < 2; ++sp)
; #pragma unroll
;                 for (int k = 0; k < 4; ++k) {
;                     const bf16x8 vf = *(const bf16x8*)(cV + (kb >> 1) * DA_VSUB + (32 * k + r) * DA_VP + (32 * (kb & 1) + 16 * sp + 8 * h2) * 2);
;                     O[k] = __builtin_amdgcn_mfma_f32_32x32x16_bf16(vf, pb[sp], O[k], 0, 0, 0);
;                 }
	v_mfma_f32_32x32x16_bf16 v[0:15], v[222:225], v[126:129], v[0:15]
	ds_read_b128 v[226:229], v235 offset:18496
	ds_read_b128 v[230:233], v235 offset:23104
	ds_read_b128 v[174:177], v235 offset:27712
	ds_read_b128 v[246:249], v235 offset:32320
	v_max_f32_e32 v241, v82, v83
	v_max3_f32 v241, v241, v84, v85
	v_max3_f32 v241, v241, v86, v87
	v_max3_f32 v241, v241, v88, v89
	v_max3_f32 v241, v241, v90, v91
	v_max3_f32 v241, v241, v92, v93
	v_max3_f32 v241, v241, v94, v95
	v_max3_f32 v241, v241, v96, v97
	v_max3_f32 v241, v241, v98, v99
	v_max3_f32 v241, v241, v100, v101
	v_max3_f32 v241, v241, v102, v103
	v_max3_f32 v241, v241, v104, v105
	v_max3_f32 v241, v241, v106, v107
	v_max3_f32 v241, v241, v108, v109
	v_max3_f32 v241, v241, v110, v111
	v_max3_f32 v241, v241, v112, v113
	v_max3_f32 v241, v241, v16, v17
	v_max3_f32 v241, v241, v18, v19
	v_max3_f32 v241, v241, v20, v21
	v_max3_f32 v241, v241, v22, v23
	v_max3_f32 v241, v241, v24, v25
	v_max3_f32 v241, v241, v26, v27
	v_max3_f32 v241, v241, v28, v29
	v_max3_f32 v241, v241, v30, v31
	v_max3_f32 v241, v241, v0, v1
	v_max3_f32 v241, v241, v2, v3
	v_max3_f32 v241, v241, v4, v5
	v_max3_f32 v241, v241, v6, v7
	v_max3_f32 v241, v241, v8, v9
	v_max3_f32 v241, v241, v10, v11
	v_max3_f32 v241, v241, v12, v13
	v_max3_f32 v241, v241, v14, v15
	ds_bpermute_b32 v242, v244, v241
	v_mov_b32_e32 v191, 0
	v_mov_b32_e32 v192, 0
	s_waitcnt lgkmcnt(0)
	v_max_f32_e32 v241, v241, v242
	v_max_f32_e32 v169, 0xf149f2ca, v241
	v_sub_f32_e32 v0, v0, v169
	v_sub_f32_e32 v1, v1, v169
	v_sub_f32_e32 v2, v2, v169
	v_sub_f32_e32 v3, v3, v169
	v_exp_f32_e32 v0, v0
	v_exp_f32_e32 v1, v1
	v_exp_f32_e32 v2, v2
	v_exp_f32_e32 v3, v3
	v_add_f32_e32 v191, v191, v0
	v_add_f32_e32 v192, v192, v1
	v_cvt_pk_bf16_f32 v194, v0, v1
	v_add_f32_e32 v191, v191, v2
	v_add_f32_e32 v192, v192, v3
	v_cvt_pk_bf16_f32 v195, v2, v3
	v_sub_f32_e32 v4, v4, v169
	v_sub_f32_e32 v5, v5, v169
	v_sub_f32_e32 v6, v6, v169
	v_sub_f32_e32 v7, v7, v169
	v_exp_f32_e32 v4, v4
	v_exp_f32_e32 v5, v5
	v_exp_f32_e32 v6, v6
	v_exp_f32_e32 v7, v7
	v_add_f32_e32 v191, v191, v4
	v_add_f32_e32 v192, v192, v5
	v_cvt_pk_bf16_f32 v196, v4, v5
	v_add_f32_e32 v191, v191, v6
	v_add_f32_e32 v192, v192, v7
	v_cvt_pk_bf16_f32 v197, v6, v7
	v_sub_f32_e32 v8, v8, v169
	v_sub_f32_e32 v9, v9, v169
	v_sub_f32_e32 v10, v10, v169
	v_sub_f32_e32 v11, v11, v169
	v_exp_f32_e32 v8, v8
	v_exp_f32_e32 v9, v9
	v_exp_f32_e32 v10, v10
	v_exp_f32_e32 v11, v11
	v_add_f32_e32 v191, v191, v8
	v_add_f32_e32 v192, v192, v9
	v_cvt_pk_bf16_f32 v198, v8, v9
	v_add_f32_e32 v191, v191, v10
	v_add_f32_e32 v192, v192, v11
	v_cvt_pk_bf16_f32 v199, v10, v11
	v_sub_f32_e32 v12, v12, v169
	v_sub_f32_e32 v13, v13, v169
	v_sub_f32_e32 v14, v14, v169
	v_sub_f32_e32 v15, v15, v169
	v_exp_f32_e32 v12, v12
	v_exp_f32_e32 v13, v13
	v_exp_f32_e32 v14, v14
	v_exp_f32_e32 v15, v15
	v_add_f32_e32 v191, v191, v12
	v_add_f32_e32 v192, v192, v13
	v_cvt_pk_bf16_f32 v200, v12, v13
	v_add_f32_e32 v191, v191, v14
	v_add_f32_e32 v192, v192, v15
	v_cvt_pk_bf16_f32 v201, v14, v15
	v_sub_f32_e32 v16, v16, v169
	v_sub_f32_e32 v17, v17, v169
	v_sub_f32_e32 v18, v18, v169
	v_sub_f32_e32 v19, v19, v169
	v_exp_f32_e32 v16, v16
	v_exp_f32_e32 v17, v17
	v_exp_f32_e32 v18, v18
	v_exp_f32_e32 v19, v19
	v_add_f32_e32 v191, v191, v16
	v_add_f32_e32 v192, v192, v17
	v_cvt_pk_bf16_f32 v202, v16, v17
	v_add_f32_e32 v191, v191, v18
	v_add_f32_e32 v192, v192, v19
	v_cvt_pk_bf16_f32 v203, v18, v19
	v_sub_f32_e32 v20, v20, v169
	v_sub_f32_e32 v21, v21, v169
	v_sub_f32_e32 v22, v22, v169
	v_sub_f32_e32 v23, v23, v169
	v_exp_f32_e32 v20, v20
	v_exp_f32_e32 v21, v21
	v_exp_f32_e32 v22, v22
	v_exp_f32_e32 v23, v23
	v_add_f32_e32 v191, v191, v20
	v_add_f32_e32 v192, v192, v21
	v_cvt_pk_bf16_f32 v204, v20, v21
	v_add_f32_e32 v191, v191, v22
	v_add_f32_e32 v192, v192, v23
	v_cvt_pk_bf16_f32 v205, v22, v23
	v_sub_f32_e32 v24, v24, v169
	v_sub_f32_e32 v25, v25, v169
	v_sub_f32_e32 v26, v26, v169
	v_sub_f32_e32 v27, v27, v169
	v_exp_f32_e32 v24, v24
	v_exp_f32_e32 v25, v25
	v_exp_f32_e32 v26, v26
	v_exp_f32_e32 v27, v27
	v_add_f32_e32 v191, v191, v24
	v_add_f32_e32 v192, v192, v25
	v_cvt_pk_bf16_f32 v206, v24, v25
	v_add_f32_e32 v191, v191, v26
	v_add_f32_e32 v192, v192, v27
	v_cvt_pk_bf16_f32 v207, v26, v27
	v_sub_f32_e32 v28, v28, v169
	v_sub_f32_e32 v29, v29, v169
	v_sub_f32_e32 v30, v30, v169
	v_sub_f32_e32 v31, v31, v169
	v_exp_f32_e32 v28, v28
	v_exp_f32_e32 v29, v29
	v_exp_f32_e32 v30, v30
	v_exp_f32_e32 v31, v31
	v_add_f32_e32 v191, v191, v28
	v_add_f32_e32 v192, v192, v29
	v_cvt_pk_bf16_f32 v208, v28, v29
	v_add_f32_e32 v191, v191, v30
	v_add_f32_e32 v192, v192, v31
	v_cvt_pk_bf16_f32 v209, v30, v31
	v_mfma_f32_32x32x16_bf16 v[48:63], v[226:229], v[194:197], 0
	ds_read_b128 v[226:229], v235 offset:18528
	v_sub_f32_e32 v98, v98, v169
	v_sub_f32_e32 v99, v99, v169
	v_sub_f32_e32 v100, v100, v169
	v_sub_f32_e32 v101, v101, v169
	v_exp_f32_e32 v98, v98
	v_exp_f32_e32 v99, v99
	v_exp_f32_e32 v100, v100
	v_exp_f32_e32 v101, v101
	v_mfma_f32_32x32x16_bf16 v[32:47], v[230:233], v[194:197], 0
	ds_read_b128 v[230:233], v235 offset:23136
	v_add_f32_e32 v191, v191, v98
	v_add_f32_e32 v192, v192, v99
	v_cvt_pk_bf16_f32 v210, v98, v99
	v_add_f32_e32 v191, v191, v100
	v_add_f32_e32 v192, v192, v101
	v_cvt_pk_bf16_f32 v211, v100, v101
	v_sub_f32_e32 v102, v102, v169
	v_sub_f32_e32 v103, v103, v169
	v_sub_f32_e32 v104, v104, v169
	v_sub_f32_e32 v105, v105, v169
	v_exp_f32_e32 v102, v102
	v_mfma_f32_32x32x16_bf16 v[16:31], v[174:177], v[194:197], 0
	ds_read_b128 v[174:177], v235 offset:27744
	v_exp_f32_e32 v103, v103
	v_exp_f32_e32 v104, v104
	v_exp_f32_e32 v105, v105
	v_add_f32_e32 v191, v191, v102
	v_add_f32_e32 v192, v192, v103
	v_cvt_pk_bf16_f32 v212, v102, v103
	v_add_f32_e32 v191, v191, v104
	v_add_f32_e32 v192, v192, v105
	v_cvt_pk_bf16_f32 v213, v104, v105
	v_mfma_f32_32x32x16_bf16 v[0:15], v[246:249], v[194:197], 0
	ds_read_b128 v[246:249], v235 offset:32352
	v_sub_f32_e32 v106, v106, v169
	v_sub_f32_e32 v107, v107, v169
	v_sub_f32_e32 v108, v108, v169
	v_sub_f32_e32 v109, v109, v169
	v_exp_f32_e32 v106, v106
	v_exp_f32_e32 v107, v107
	v_exp_f32_e32 v108, v108
	v_exp_f32_e32 v109, v109
	s_waitcnt lgkmcnt(3)
; __device__ __forceinline__ float fast_exp2(float x) { return __builtin_amdgcn_exp2f(x); }
; __device__ void da_unit(char* lds, const Params& p, int layer, int unit) {
;     ...
;                 lrow *= alpha; mrow = mnew;
;             }
;             const float mm = mrow - A;
;             float ps = 0.f;
; #pragma unroll
;             for (int e = 0; e < 16; ++e) { s[e] = fast_exp2(s[e] - mm); ps += s[e]; }
;             lrow += ps;
;             bf16x8 pb[2];
; #pragma unroll
;             for (int sp = 0; sp < 2; ++sp) {
;                 u32x4 w;
;                 w.x = cvt_pk_bf16(s[8 * sp + 0], s[8 * sp + 1]); w.y = cvt_pk_bf16(s[8 * sp + 2], s[8 * sp + 3]);
;                 w.z = cvt_pk_bf16(s[8 * sp + 4], s[8 * sp + 5]); w.w = cvt_pk_bf16(s[8 * sp + 6], s[8 * sp + 7]);
;                 pb[sp] = __builtin_bit_cast(bf16x8, w);
;             }
; #pragma unroll
;             for (int sp = 0; sp < 2; ++sp)
; #pragma unroll
;                 for (int k = 0; k < 4; ++k) {
;                     const bf16x8 vf = *(const bf16x8*)(cV + (kb >> 1) * DA_VSUB + (32 * k + r) * DA_VP + (32 * (kb & 1) + 16 * sp + 8 * h2) * 2);
;                     O[k] = __builtin_amdgcn_mfma_f32_32x32x16_bf16(vf, pb[sp], O[k], 0, 0, 0);
;                 }
;         }
;         if (it + 1 < NT) {
; #pragma unroll
;             for (int j = 0; j < 4; ++j) {
;                 *(u32x4*)(nK + (kr_ + 32 * j) * DA_KP + kc_ * 16) = rk[j];
;                 *(u32x4*)(nK + DA_KBYTES + (j >> 1) * DA_VSUB + (vr_ + 64 * (j & 1)) * DA_VP + vc_ * 16) = rv[j];
;             }
;         }
;         __syncthreads();
;     }
	v_mfma_f32_32x32x16_bf16 v[48:63], v[226:229], v[198:201], v[48:63]
	ds_read_b128 v[226:229], v235 offset:18432
	v_add_f32_e32 v191, v191, v106
	v_add_f32_e32 v192, v192, v107
	v_cvt_pk_bf16_f32 v214, v106, v107
	v_add_f32_e32 v191, v191, v108
	v_add_f32_e32 v192, v192, v109
	v_cvt_pk_bf16_f32 v215, v108, v109
	s_waitcnt lgkmcnt(3)
	v_mfma_f32_32x32x16_bf16 v[32:47], v[230:233], v[198:201], v[32:47]
	ds_read_b128 v[230:233], v235 offset:23040
	v_sub_f32_e32 v110, v110, v169
	v_sub_f32_e32 v111, v111, v169
	v_sub_f32_e32 v112, v112, v169
	v_sub_f32_e32 v113, v113, v169
	v_exp_f32_e32 v110, v110
	s_waitcnt lgkmcnt(3)
	v_mfma_f32_32x32x16_bf16 v[16:31], v[174:177], v[198:201], v[16:31]
	ds_read_b128 v[174:177], v235 offset:27648
	v_exp_f32_e32 v111, v111
	v_exp_f32_e32 v112, v112
	v_exp_f32_e32 v113, v113
	s_waitcnt lgkmcnt(3)
	v_mfma_f32_32x32x16_bf16 v[0:15], v[246:249], v[198:201], v[0:15]
	ds_read_b128 v[246:249], v235 offset:32256
	v_add_f32_e32 v191, v191, v110
	v_add_f32_e32 v192, v192, v111
	v_cvt_pk_bf16_f32 v216, v110, v111
	v_add_f32_e32 v191, v191, v112
	v_add_f32_e32 v192, v192, v113
	v_cvt_pk_bf16_f32 v217, v112, v113
	s_waitcnt lgkmcnt(3)
	v_mfma_f32_32x32x16_bf16 v[48:63], v[226:229], v[202:205], v[48:63]
	ds_read_b128 v[226:229], v235 offset:18464
	v_sub_f32_e32 v82, v82, v169
	v_sub_f32_e32 v83, v83, v169
	v_sub_f32_e32 v84, v84, v169
	v_sub_f32_e32 v85, v85, v169
	v_exp_f32_e32 v82, v82
	v_exp_f32_e32 v83, v83
	v_exp_f32_e32 v84, v84
	v_exp_f32_e32 v85, v85
	s_waitcnt lgkmcnt(3)
	v_mfma_f32_32x32x16_bf16 v[32:47], v[230:233], v[202:205], v[32:47]
	ds_read_b128 v[230:233], v235 offset:23072
	v_add_f32_e32 v191, v191, v82
	v_add_f32_e32 v192, v192, v83
	v_cvt_pk_bf16_f32 v218, v82, v83
	v_add_f32_e32 v191, v191, v84
	v_add_f32_e32 v192, v192, v85
	v_cvt_pk_bf16_f32 v219, v84, v85
	v_sub_f32_e32 v86, v86, v169
	v_sub_f32_e32 v87, v87, v169
	v_sub_f32_e32 v88, v88, v169
	v_sub_f32_e32 v89, v89, v169
	v_exp_f32_e32 v86, v86
	s_waitcnt lgkmcnt(3)
	v_mfma_f32_32x32x16_bf16 v[16:31], v[174:177], v[202:205], v[16:31]
	ds_read_b128 v[174:177], v235 offset:27680
	v_exp_f32_e32 v87, v87
	v_exp_f32_e32 v88, v88
	v_exp_f32_e32 v89, v89
	v_add_f32_e32 v191, v191, v86
	v_add_f32_e32 v192, v192, v87
	v_cvt_pk_bf16_f32 v220, v86, v87
	v_add_f32_e32 v191, v191, v88
	v_add_f32_e32 v192, v192, v89
	v_cvt_pk_bf16_f32 v221, v88, v89
	s_waitcnt lgkmcnt(3)
	v_mfma_f32_32x32x16_bf16 v[0:15], v[246:249], v[202:205], v[0:15]
	ds_read_b128 v[246:249], v235 offset:32288
	v_sub_f32_e32 v90, v90, v169
	v_sub_f32_e32 v91, v91, v169
	v_sub_f32_e32 v92, v92, v169
	v_sub_f32_e32 v93, v93, v169
	v_exp_f32_e32 v90, v90
	v_exp_f32_e32 v91, v91
	v_exp_f32_e32 v92, v92
	v_exp_f32_e32 v93, v93
	s_waitcnt lgkmcnt(3)
	v_mfma_f32_32x32x16_bf16 v[48:63], v[226:229], v[206:209], v[48:63]
	ds_read_b128 v[226:229], v235 offset:64
	v_add_f32_e32 v191, v191, v90
	v_add_f32_e32 v192, v192, v91
	v_cvt_pk_bf16_f32 v222, v90, v91
	v_add_f32_e32 v191, v191, v92
	v_add_f32_e32 v192, v192, v93
	v_cvt_pk_bf16_f32 v223, v92, v93
	s_waitcnt lgkmcnt(3)
	v_mfma_f32_32x32x16_bf16 v[32:47], v[230:233], v[206:209], v[32:47]
	ds_read_b128 v[230:233], v235 offset:4672
	v_sub_f32_e32 v94, v94, v169
	v_sub_f32_e32 v95, v95, v169
	v_sub_f32_e32 v96, v96, v169
	v_sub_f32_e32 v97, v97, v169
	v_exp_f32_e32 v94, v94
	s_waitcnt lgkmcnt(3)
	v_mfma_f32_32x32x16_bf16 v[16:31], v[174:177], v[206:209], v[16:31]
	ds_read_b128 v[174:177], v235 offset:9280
	v_exp_f32_e32 v95, v95
	v_exp_f32_e32 v96, v96
	v_exp_f32_e32 v97, v97
	s_waitcnt lgkmcnt(3)
	v_mfma_f32_32x32x16_bf16 v[0:15], v[246:249], v[206:209], v[0:15]
	ds_read_b128 v[246:249], v235 offset:13888
	v_add_f32_e32 v191, v191, v94
	v_add_f32_e32 v192, v192, v95
	v_cvt_pk_bf16_f32 v224, v94, v95
	v_add_f32_e32 v191, v191, v96
	v_add_f32_e32 v192, v192, v97
	v_cvt_pk_bf16_f32 v225, v96, v97
	s_waitcnt lgkmcnt(3)
	v_mfma_f32_32x32x16_bf16 v[48:63], v[226:229], v[210:213], v[48:63]
	ds_read_b128 v[226:229], v235 offset:96
	s_waitcnt lgkmcnt(3)
	v_mfma_f32_32x32x16_bf16 v[32:47], v[230:233], v[210:213], v[32:47]
	ds_read_b128 v[230:233], v235 offset:4704
	s_waitcnt lgkmcnt(3)
	v_mfma_f32_32x32x16_bf16 v[16:31], v[174:177], v[210:213], v[16:31]
	ds_read_b128 v[174:177], v235 offset:9312
	s_waitcnt lgkmcnt(3)
	v_mfma_f32_32x32x16_bf16 v[0:15], v[246:249], v[210:213], v[0:15]
	ds_read_b128 v[246:249], v235 offset:13920
	s_waitcnt lgkmcnt(3)
	v_mfma_f32_32x32x16_bf16 v[48:63], v[226:229], v[214:217], v[48:63]
	ds_read_b128 v[226:229], v235 offset:0
	s_waitcnt lgkmcnt(3)
	v_mfma_f32_32x32x16_bf16 v[32:47], v[230:233], v[214:217], v[32:47]
	ds_read_b128 v[230:233], v235 offset:4608
	s_waitcnt lgkmcnt(3)
	v_mfma_f32_32x32x16_bf16 v[16:31], v[174:177], v[214:217], v[16:31]
	ds_read_b128 v[174:177], v235 offset:9216
	s_waitcnt lgkmcnt(3)
	v_mfma_f32_32x32x16_bf16 v[0:15], v[246:249], v[214:217], v[0:15]
	ds_read_b128 v[246:249], v235 offset:13824
	s_waitcnt lgkmcnt(3)
	v_mfma_f32_32x32x16_bf16 v[48:63], v[226:229], v[218:221], v[48:63]
	ds_read_b128 v[226:229], v235 offset:32
	s_waitcnt lgkmcnt(3)
	v_mfma_f32_32x32x16_bf16 v[32:47], v[230:233], v[218:221], v[32:47]
	ds_read_b128 v[230:233], v235 offset:4640
	s_waitcnt lgkmcnt(3)
	v_mfma_f32_32x32x16_bf16 v[16:31], v[174:177], v[218:221], v[16:31]
	ds_read_b128 v[174:177], v235 offset:9248
	s_waitcnt lgkmcnt(3)
	v_mfma_f32_32x32x16_bf16 v[0:15], v[246:249], v[218:221], v[0:15]
	ds_read_b128 v[246:249], v235 offset:13856
	s_waitcnt lgkmcnt(3)
	v_mfma_f32_32x32x16_bf16 v[48:63], v[226:229], v[222:225], v[48:63]
	s_waitcnt lgkmcnt(2)
	v_mfma_f32_32x32x16_bf16 v[32:47], v[230:233], v[222:225], v[32:47]
	s_waitcnt lgkmcnt(1)
	v_mfma_f32_32x32x16_bf16 v[16:31], v[174:177], v[222:225], v[16:31]
	s_waitcnt lgkmcnt(0)
	v_mfma_f32_32x32x16_bf16 v[0:15], v[246:249], v[222:225], v[0:15]
	v_add_f32_e32 v193, v191, v192
	s_mov_b32 s2, 0x11800
	v_add3_u32 v158, s2, v180, v182
	s_waitcnt vmcnt(7)
	ds_write_b128 v158, v[130:133] offset:0
	s_waitcnt vmcnt(6)
	ds_write_b128 v158, v[134:137] offset:8704
	s_waitcnt vmcnt(5)
	ds_write_b128 v158, v[138:141] offset:17408
	s_waitcnt vmcnt(4)
	ds_write_b128 v158, v[142:145] offset:26112
	v_add3_u32 v242, s2, v183, v181
	s_waitcnt vmcnt(3)
	ds_write_b128 v242, v[66:69] offset:34816
	s_waitcnt vmcnt(2)
	ds_write_b128 v242, v[70:73] offset:44032
	s_waitcnt vmcnt(1)
	ds_write_b128 v242, v[74:77] offset:53248
	s_waitcnt vmcnt(0)
	ds_write_b128 v242, v[78:81] offset:62464
	s_sub_i32 s9, 16, s14
	s_waitcnt lgkmcnt(0)
	s_barrier
; __device__ void da_unit(char* lds, const Params& p, int layer, int unit) {
;     ...
;     for (int e = 0; e < 16; ++e) Bs[e] = -slope2 * (float)(16 * (e >> 3) + (e & 7));
;     float mrow = -1e30f, lrow = 0.f;
;     const float qrel = (float)(8 * h2) - (float)(q0 + r);
;     ...
; #pragma unroll
;     for (int e = 0; e < 16; ++e) Bs[e] = -Bs[e];
	v_mul_f32_e32 v66, 0x80000000, v65
	v_mul_f32_e32 v68, -2.0, v65
	v_mul_f32_e32 v69, 0xc0400000, v65
	v_mul_f32_e32 v70, -4.0, v65
	v_mul_f32_e32 v71, 0xc0a00000, v65
	v_mul_f32_e32 v72, 0xc0c00000, v65
	v_mul_f32_e32 v73, 0xc0e00000, v65
	v_mul_f32_e32 v74, 0xc1800000, v65
	v_mul_f32_e32 v75, 0xc1880000, v65
	v_mul_f32_e32 v76, 0xc1900000, v65
	v_mul_f32_e32 v77, 0xc1980000, v65
	v_mul_f32_e32 v78, 0xc1a00000, v65
	v_mul_f32_e32 v79, 0xc1a80000, v65
	v_mul_f32_e32 v80, 0xc1b00000, v65
	v_mul_f32_e32 v81, 0xc1b80000, v65
	v_xor_b32_e32 v67, 0x80000000, v65
	v_mul_f32_e32 v64, 0xc2000000, v65
	v_mov_b32_e32 v250, v65
	v_mov_b32_e32 v191, 0
	v_mov_b32_e32 v192, 0
	v_mov_b32_e32 v202, 0
	v_mov_b32_e32 v203, 0
	v_mov_b32_e32 v204, 0
	v_mov_b32_e32 v205, 0
	v_mov_b32_e32 v206, 0
	v_mov_b32_e32 v207, 0
	v_mov_b32_e32 v208, 0
	v_mov_b32_e32 v209, 0
	s_cmp_lg_u32 s9, 1
	s_cbranch_scc1 .Lda_p_noflip
	v_xor_b32_e32 v66, 0x80000000, v66
	v_xor_b32_e32 v67, 0x80000000, v67
	v_xor_b32_e32 v68, 0x80000000, v68
	v_xor_b32_e32 v69, 0x80000000, v69
	v_xor_b32_e32 v70, 0x80000000, v70
	v_xor_b32_e32 v71, 0x80000000, v71
	v_xor_b32_e32 v72, 0x80000000, v72
	v_xor_b32_e32 v73, 0x80000000, v73
	v_xor_b32_e32 v74, 0x80000000, v74
	v_xor_b32_e32 v75, 0x80000000, v75
	v_xor_b32_e32 v76, 0x80000000, v76
	v_xor_b32_e32 v77, 0x80000000, v77
	v_xor_b32_e32 v78, 0x80000000, v78
	v_xor_b32_e32 v79, 0x80000000, v79
	v_xor_b32_e32 v80, 0x80000000, v80
	v_xor_b32_e32 v81, 0x80000000, v81
